# v28 + out-proj epilogue (bf16 residual): residual pieces of two 16-row groups loaded together (4 loads in flight), second group via dead registers v240-247
# speedup vs baseline: 1.0127x; 1.0127x over previous
.LBB0_601:
	s_or_b64 exec, exec, s[22:23]
	s_lshl_b32 s4, s42, 5
	v_readlane_b32 s36, v254, 10
	s_lshl_b32 s5, s12, 8
	s_lshl_b32 s64, s93, 11
	v_readlane_b32 s40, v254, 14
	v_readlane_b32 s41, v254, 15
	v_readlane_b32 s44, v254, 18
	v_readlane_b32 s45, v254, 19
	v_readlane_b32 s46, v254, 20
	v_readlane_b32 s47, v254, 21
	v_readlane_b32 s48, v254, 22
	v_readlane_b32 s49, v254, 23
	v_lshrrev_b32_e32 v128, 1, v142
	s_or_b32 s4, s5, s4
	s_lshl_b64 s[56:57], s[64:65], 2
	v_readlane_b32 s37, v254, 11
	v_readlane_b32 s38, v254, 12
	v_readlane_b32 s39, v254, 13
	s_mov_b64 s[48:49], s[40:41]
	v_and_or_b32 v174, v128, 24, s4
	s_add_u32 s4, s48, s56
	s_addc_u32 s5, s49, s57
	v_ashrrev_i32_e32 v175, 31, v174
	s_waitcnt lgkmcnt(0)
	s_barrier
	v_lshl_add_u64 v[132:133], v[174:175], 2, s[4:5]
	global_load_dwordx4 v[136:139], v[132:133], off offset:16
	global_load_dwordx4 v[140:143], v[132:133], off
	global_load_dwordx4 v[128:131], v[132:133], off offset:528
	s_nop 0
	global_load_dwordx4 v[132:135], v[132:133], off offset:512
	v_lshl_add_u32 v237, v188, 2, 0
	ds_read_b32 v160, v237 offset:4096
	v_add_u32_e32 v220, s26, v188
	v_ashrrev_i32_e32 v221, 31, v220
	v_lshlrev_b64 v[144:145], 11, v[220:221]
	v_readlane_b32 s4, v255, 14
	s_cmp_lg_u32 s93, 0
	v_lshl_add_u64 v[164:165], v[144:145], 0, v[174:175]
	v_readlane_b32 s5, v255, 15
	s_cselect_b64 s[24:25], -1, 0
	s_cmp_eq_u32 s93, 0
	v_lshl_add_u64 v[168:169], v[164:165], 1, s[4:5]
	v_readlane_b32 s42, v254, 16
	v_readlane_b32 s43, v254, 17
	v_readlane_b32 s50, v254, 24
	v_readlane_b32 s51, v254, 25
	s_mov_b64 s[46:47], s[38:39]
	s_mov_b64 s[44:45], s[36:37]
	s_cbranch_scc1 .LBB0_680
	s_mov_b64 s[100:101], 0x10000
	global_load_dwordx4 v[144:147], v[168:169], off
	global_load_dwordx4 v[152:155], v[168:169], off offset:256
	v_lshl_add_u64 v[252:253], v[168:169], 0, s[100:101]
	global_load_dwordx4 v[240:243], v[252:253], off
	global_load_dwordx4 v[244:247], v[252:253], off offset:256
	s_waitcnt vmcnt(3)
	v_lshlrev_b32_e32 v148, 16, v144
	v_and_b32_e32 v149, 0xffff0000, v144
	v_lshlrev_b32_e32 v150, 16, v145
	v_and_b32_e32 v151, 0xffff0000, v145
	v_lshlrev_b32_e32 v144, 16, v146
	v_and_b32_e32 v145, 0xffff0000, v146
	v_lshlrev_b32_e32 v146, 16, v147
	v_and_b32_e32 v147, 0xffff0000, v147
	s_cbranch_execnz .LBB0_604

.LBB0_604:
	v_readlane_b32 s4, v255, 14
	v_or_b32_e32 v166, 0x80, v164
	v_mov_b32_e32 v167, v165
	v_readlane_b32 s5, v255, 15
	s_and_b64 vcc, exec, s[24:25]
	s_nop 0
	v_lshl_add_u64 v[172:173], v[166:167], 1, s[4:5]
	s_cbranch_vccz .LBB0_681
	s_waitcnt vmcnt(2)
	v_lshlrev_b32_e32 v156, 16, v152
	v_and_b32_e32 v157, 0xffff0000, v152
	v_lshlrev_b32_e32 v158, 16, v153
	v_and_b32_e32 v159, 0xffff0000, v153
	v_lshlrev_b32_e32 v152, 16, v154
	v_and_b32_e32 v153, 0xffff0000, v154
	v_lshlrev_b32_e32 v154, 16, v155
	v_and_b32_e32 v155, 0xffff0000, v155
	s_cbranch_execnz .LBB0_607

.LBB0_607:
	s_waitcnt lgkmcnt(0)
	v_pk_mul_f32 v[120:121], v[120:121], v[160:161] op_sel_hi:[1,0]
	v_pk_mul_f32 v[122:123], v[122:123], v[160:161] op_sel_hi:[1,0]
	v_pk_mul_f32 v[124:125], v[124:125], v[160:161] op_sel_hi:[1,0]
	v_pk_mul_f32 v[126:127], v[126:127], v[160:161] op_sel_hi:[1,0]
	v_pk_mul_f32 v[108:109], v[108:109], v[160:161] op_sel_hi:[1,0]
	v_pk_mul_f32 v[110:111], v[110:111], v[160:161] op_sel_hi:[1,0]
	v_pk_mul_f32 v[116:117], v[116:117], v[160:161] op_sel_hi:[1,0]
	v_pk_mul_f32 v[118:119], v[118:119], v[160:161] op_sel_hi:[1,0]
	s_waitcnt vmcnt(0)
	v_pk_fma_f32 v[122:123], v[142:143], v[122:123], v[150:151]
	v_pk_fma_f32 v[120:121], v[140:141], v[120:121], v[148:149]
	v_pk_fma_f32 v[126:127], v[138:139], v[126:127], v[146:147]
	v_pk_fma_f32 v[124:125], v[136:137], v[124:125], v[144:145]
	v_pk_fma_f32 v[110:111], v[134:135], v[110:111], v[158:159]
	v_pk_fma_f32 v[108:109], v[132:133], v[108:109], v[156:157]
	v_pk_fma_f32 v[118:119], v[130:131], v[118:119], v[154:155]
	v_pk_fma_f32 v[116:117], v[128:129], v[116:117], v[152:153]
	v_add3_u32 v144, s26, v188, 16
	ds_read_b32 v160, v237 offset:4160
	v_ashrrev_i32_e32 v145, 31, v144
	v_lshlrev_b64 v[144:145], 11, v[144:145]
	v_readlane_b32 s4, v255, 14
	v_lshl_add_u64 v[170:171], v[144:145], 0, v[174:175]
	v_readlane_b32 s5, v255, 15
	s_and_b64 vcc, exec, s[24:25]
	s_nop 0
	v_lshl_add_u64 v[178:179], v[170:171], 1, s[4:5]
	s_cbranch_vccz .LBB0_682
	s_waitcnt vmcnt(1)
	v_mov_b32_e32 v144, v240
	v_mov_b32_e32 v145, v241
	v_mov_b32_e32 v146, v242
	v_mov_b32_e32 v147, v243
	v_lshlrev_b32_e32 v148, 16, v144
	v_and_b32_e32 v149, 0xffff0000, v144
	v_lshlrev_b32_e32 v150, 16, v145
	v_and_b32_e32 v151, 0xffff0000, v145
	v_lshlrev_b32_e32 v144, 16, v146
	v_and_b32_e32 v145, 0xffff0000, v146
	v_lshlrev_b32_e32 v146, 16, v147
	v_and_b32_e32 v147, 0xffff0000, v147
	s_cbranch_execnz .LBB0_610

.LBB0_610:
	v_readlane_b32 s4, v255, 14
	v_or_b32_e32 v176, 0x80, v170
	v_mov_b32_e32 v177, v171
	v_readlane_b32 s5, v255, 15
	s_and_b64 vcc, exec, s[24:25]
	s_nop 0
	v_lshl_add_u64 v[180:181], v[176:177], 1, s[4:5]
	s_cbranch_vccz .LBB0_683
	s_waitcnt vmcnt(0)
	v_mov_b32_e32 v152, v244
	v_mov_b32_e32 v153, v245
	v_mov_b32_e32 v154, v246
	v_mov_b32_e32 v155, v247
	v_lshlrev_b32_e32 v156, 16, v152
	v_and_b32_e32 v157, 0xffff0000, v152
	v_lshlrev_b32_e32 v158, 16, v153
	v_and_b32_e32 v159, 0xffff0000, v153
	v_lshlrev_b32_e32 v152, 16, v154
	v_and_b32_e32 v153, 0xffff0000, v154
	v_lshlrev_b32_e32 v154, 16, v155
	v_and_b32_e32 v155, 0xffff0000, v155
	s_cbranch_execnz .LBB0_613

.LBB0_613:
	s_waitcnt lgkmcnt(0)
	v_pk_mul_f32 v[112:113], v[112:113], v[160:161] op_sel_hi:[1,0]
	v_pk_mul_f32 v[114:115], v[114:115], v[160:161] op_sel_hi:[1,0]
	v_pk_mul_f32 v[104:105], v[104:105], v[160:161] op_sel_hi:[1,0]
	v_pk_mul_f32 v[106:107], v[106:107], v[160:161] op_sel_hi:[1,0]
	v_pk_mul_f32 v[100:101], v[100:101], v[160:161] op_sel_hi:[1,0]
	v_pk_mul_f32 v[102:103], v[102:103], v[160:161] op_sel_hi:[1,0]
	v_pk_mul_f32 v[96:97], v[96:97], v[160:161] op_sel_hi:[1,0]
	v_pk_mul_f32 v[98:99], v[98:99], v[160:161] op_sel_hi:[1,0]
	s_waitcnt vmcnt(0)
	v_pk_fma_f32 v[114:115], v[142:143], v[114:115], v[150:151]
	v_pk_fma_f32 v[112:113], v[140:141], v[112:113], v[148:149]
	v_pk_fma_f32 v[106:107], v[138:139], v[106:107], v[146:147]
	v_pk_fma_f32 v[104:105], v[136:137], v[104:105], v[144:145]
	v_pk_fma_f32 v[102:103], v[134:135], v[102:103], v[158:159]
	v_pk_fma_f32 v[100:101], v[132:133], v[100:101], v[156:157]
	v_pk_fma_f32 v[98:99], v[130:131], v[98:99], v[154:155]
	v_pk_fma_f32 v[96:97], v[128:129], v[96:97], v[152:153]
	v_add3_u32 v144, s26, v188, 32
	ds_read_b32 v160, v237 offset:4224
	v_ashrrev_i32_e32 v145, 31, v144
	v_lshlrev_b64 v[144:145], 11, v[144:145]
	v_readlane_b32 s4, v255, 14
	v_lshl_add_u64 v[182:183], v[144:145], 0, v[174:175]
	v_readlane_b32 s5, v255, 15
	s_and_b64 vcc, exec, s[24:25]
	s_nop 0
	v_lshl_add_u64 v[186:187], v[182:183], 1, s[4:5]
	s_cbranch_vccz .LBB0_684
	global_load_dwordx4 v[144:147], v[186:187], off
	global_load_dwordx4 v[152:155], v[186:187], off offset:256
	v_lshl_add_u64 v[252:253], v[186:187], 0, s[100:101]
	global_load_dwordx4 v[240:243], v[252:253], off
	global_load_dwordx4 v[244:247], v[252:253], off offset:256
	s_waitcnt vmcnt(3)
	v_lshlrev_b32_e32 v148, 16, v144
	v_and_b32_e32 v149, 0xffff0000, v144
	v_lshlrev_b32_e32 v150, 16, v145
	v_and_b32_e32 v151, 0xffff0000, v145
	v_lshlrev_b32_e32 v144, 16, v146
	v_and_b32_e32 v145, 0xffff0000, v146
	v_lshlrev_b32_e32 v146, 16, v147
	v_and_b32_e32 v147, 0xffff0000, v147
	s_cbranch_execnz .LBB0_616

.LBB0_616:
	v_readlane_b32 s4, v255, 14
	v_or_b32_e32 v184, 0x80, v182
	v_mov_b32_e32 v185, v183
	v_readlane_b32 s5, v255, 15
	s_and_b64 vcc, exec, s[24:25]
	s_nop 0
	v_lshl_add_u64 v[190:191], v[184:185], 1, s[4:5]
	s_cbranch_vccz .LBB0_685
	s_waitcnt vmcnt(2)
	v_lshlrev_b32_e32 v156, 16, v152
	v_and_b32_e32 v157, 0xffff0000, v152
	v_lshlrev_b32_e32 v158, 16, v153
	v_and_b32_e32 v159, 0xffff0000, v153
	v_lshlrev_b32_e32 v152, 16, v154
	v_and_b32_e32 v153, 0xffff0000, v154
	v_lshlrev_b32_e32 v154, 16, v155
	v_and_b32_e32 v155, 0xffff0000, v155
	s_cbranch_execnz .LBB0_619

.LBB0_619:
	s_waitcnt lgkmcnt(0)
	v_pk_mul_f32 v[92:93], v[92:93], v[160:161] op_sel_hi:[1,0]
	v_pk_mul_f32 v[94:95], v[94:95], v[160:161] op_sel_hi:[1,0]
	v_pk_mul_f32 v[88:89], v[88:89], v[160:161] op_sel_hi:[1,0]
	v_pk_mul_f32 v[90:91], v[90:91], v[160:161] op_sel_hi:[1,0]
	v_pk_mul_f32 v[84:85], v[84:85], v[160:161] op_sel_hi:[1,0]
	v_pk_mul_f32 v[86:87], v[86:87], v[160:161] op_sel_hi:[1,0]
	v_pk_mul_f32 v[80:81], v[80:81], v[160:161] op_sel_hi:[1,0]
	v_pk_mul_f32 v[82:83], v[82:83], v[160:161] op_sel_hi:[1,0]
	s_waitcnt vmcnt(0)
	v_pk_fma_f32 v[94:95], v[142:143], v[94:95], v[150:151]
	v_pk_fma_f32 v[92:93], v[140:141], v[92:93], v[148:149]
	v_pk_fma_f32 v[90:91], v[138:139], v[90:91], v[146:147]
	v_pk_fma_f32 v[88:89], v[136:137], v[88:89], v[144:145]
	v_pk_fma_f32 v[86:87], v[134:135], v[86:87], v[158:159]
	v_pk_fma_f32 v[84:85], v[132:133], v[84:85], v[156:157]
	v_pk_fma_f32 v[82:83], v[130:131], v[82:83], v[154:155]
	v_pk_fma_f32 v[80:81], v[128:129], v[80:81], v[152:153]
	v_add3_u32 v144, s26, v188, 48
	ds_read_b32 v160, v237 offset:4288
	v_ashrrev_i32_e32 v145, 31, v144
	v_lshlrev_b64 v[144:145], 11, v[144:145]
	v_readlane_b32 s4, v255, 14
	v_lshl_add_u64 v[188:189], v[144:145], 0, v[174:175]
	v_readlane_b32 s5, v255, 15
	s_and_b64 vcc, exec, s[24:25]
	s_nop 0
	v_lshl_add_u64 v[194:195], v[188:189], 1, s[4:5]
	s_cbranch_vccz .LBB0_686
	s_waitcnt vmcnt(1)
	v_mov_b32_e32 v144, v240
	v_mov_b32_e32 v145, v241
	v_mov_b32_e32 v146, v242
	v_mov_b32_e32 v147, v243
	v_lshlrev_b32_e32 v148, 16, v144
	v_and_b32_e32 v149, 0xffff0000, v144
	v_lshlrev_b32_e32 v150, 16, v145
	v_and_b32_e32 v151, 0xffff0000, v145
	v_lshlrev_b32_e32 v144, 16, v146
	v_and_b32_e32 v145, 0xffff0000, v146
	v_lshlrev_b32_e32 v146, 16, v147
	v_and_b32_e32 v147, 0xffff0000, v147
	s_cbranch_execnz .LBB0_622

.LBB0_622:
	v_readlane_b32 s4, v255, 14
	v_or_b32_e32 v192, 0x80, v188
	v_mov_b32_e32 v193, v189
	v_readlane_b32 s5, v255, 15
	s_and_b64 vcc, exec, s[24:25]
	s_nop 0
	v_lshl_add_u64 v[198:199], v[192:193], 1, s[4:5]
	s_cbranch_vccz .LBB0_687
	s_waitcnt vmcnt(0)
	v_mov_b32_e32 v152, v244
	v_mov_b32_e32 v153, v245
	v_mov_b32_e32 v154, v246
	v_mov_b32_e32 v155, v247
	v_lshlrev_b32_e32 v156, 16, v152
	v_and_b32_e32 v157, 0xffff0000, v152
	v_lshlrev_b32_e32 v158, 16, v153
	v_and_b32_e32 v159, 0xffff0000, v153
	v_lshlrev_b32_e32 v152, 16, v154
	v_and_b32_e32 v153, 0xffff0000, v154
	v_lshlrev_b32_e32 v154, 16, v155
	v_and_b32_e32 v155, 0xffff0000, v155
	s_cbranch_execnz .LBB0_625

.LBB0_625:
	s_waitcnt lgkmcnt(0)
	v_pk_mul_f32 v[76:77], v[76:77], v[160:161] op_sel_hi:[1,0]
	v_pk_mul_f32 v[78:79], v[78:79], v[160:161] op_sel_hi:[1,0]
	v_pk_mul_f32 v[72:73], v[72:73], v[160:161] op_sel_hi:[1,0]
	v_pk_mul_f32 v[74:75], v[74:75], v[160:161] op_sel_hi:[1,0]
	v_pk_mul_f32 v[68:69], v[68:69], v[160:161] op_sel_hi:[1,0]
	v_pk_mul_f32 v[70:71], v[70:71], v[160:161] op_sel_hi:[1,0]
	v_pk_mul_f32 v[64:65], v[64:65], v[160:161] op_sel_hi:[1,0]
	v_pk_mul_f32 v[66:67], v[66:67], v[160:161] op_sel_hi:[1,0]
	s_waitcnt vmcnt(0)
	v_pk_fma_f32 v[78:79], v[142:143], v[78:79], v[150:151]
	v_pk_fma_f32 v[76:77], v[140:141], v[76:77], v[148:149]
	v_pk_fma_f32 v[74:75], v[138:139], v[74:75], v[146:147]
	v_pk_fma_f32 v[72:73], v[136:137], v[72:73], v[144:145]
	v_pk_fma_f32 v[70:71], v[134:135], v[70:71], v[158:159]
	v_pk_fma_f32 v[68:69], v[132:133], v[68:69], v[156:157]
	v_pk_fma_f32 v[66:67], v[130:131], v[66:67], v[154:155]
	v_pk_fma_f32 v[64:65], v[128:129], v[64:65], v[152:153]
	v_add_u32_e32 v144, 0x80, v220
	ds_read_b32 v160, v237 offset:4608
	v_ashrrev_i32_e32 v145, 31, v144
	v_lshlrev_b64 v[144:145], 11, v[144:145]
	v_readlane_b32 s4, v255, 14
	v_lshl_add_u64 v[196:197], v[144:145], 0, v[174:175]
	v_readlane_b32 s5, v255, 15
	s_and_b64 vcc, exec, s[24:25]
	s_nop 0
	v_lshl_add_u64 v[202:203], v[196:197], 1, s[4:5]
	s_cbranch_vccz .LBB0_688
	global_load_dwordx4 v[144:147], v[202:203], off
	global_load_dwordx4 v[152:155], v[202:203], off offset:256
	v_lshl_add_u64 v[252:253], v[202:203], 0, s[100:101]
	global_load_dwordx4 v[240:243], v[252:253], off
	global_load_dwordx4 v[244:247], v[252:253], off offset:256
	s_waitcnt vmcnt(3)
	v_lshlrev_b32_e32 v148, 16, v144
	v_and_b32_e32 v149, 0xffff0000, v144
	v_lshlrev_b32_e32 v150, 16, v145
	v_and_b32_e32 v151, 0xffff0000, v145
	v_lshlrev_b32_e32 v144, 16, v146
	v_and_b32_e32 v145, 0xffff0000, v146
	v_lshlrev_b32_e32 v146, 16, v147
	v_and_b32_e32 v147, 0xffff0000, v147
	s_cbranch_execnz .LBB0_628

.LBB0_628:
	v_readlane_b32 s4, v255, 14
	v_or_b32_e32 v200, 0x80, v196
	v_mov_b32_e32 v201, v197
	v_readlane_b32 s5, v255, 15
	s_and_b64 vcc, exec, s[24:25]
	s_nop 0
	v_lshl_add_u64 v[206:207], v[200:201], 1, s[4:5]
	s_cbranch_vccz .LBB0_689
	s_waitcnt vmcnt(2)
	v_lshlrev_b32_e32 v156, 16, v152
	v_and_b32_e32 v157, 0xffff0000, v152
	v_lshlrev_b32_e32 v158, 16, v153
	v_and_b32_e32 v159, 0xffff0000, v153
	v_lshlrev_b32_e32 v152, 16, v154
	v_and_b32_e32 v153, 0xffff0000, v154
	v_lshlrev_b32_e32 v154, 16, v155
	v_and_b32_e32 v155, 0xffff0000, v155
	s_cbranch_execnz .LBB0_631

.LBB0_631:
	s_waitcnt lgkmcnt(0)
	v_pk_mul_f32 v[60:61], v[60:61], v[160:161] op_sel_hi:[1,0]
	v_pk_mul_f32 v[62:63], v[62:63], v[160:161] op_sel_hi:[1,0]
	v_pk_mul_f32 v[56:57], v[56:57], v[160:161] op_sel_hi:[1,0]
	v_pk_mul_f32 v[58:59], v[58:59], v[160:161] op_sel_hi:[1,0]
	v_pk_mul_f32 v[52:53], v[52:53], v[160:161] op_sel_hi:[1,0]
	v_pk_mul_f32 v[54:55], v[54:55], v[160:161] op_sel_hi:[1,0]
	v_pk_mul_f32 v[48:49], v[48:49], v[160:161] op_sel_hi:[1,0]
	v_pk_mul_f32 v[50:51], v[50:51], v[160:161] op_sel_hi:[1,0]
	s_waitcnt vmcnt(0)
	v_pk_fma_f32 v[62:63], v[142:143], v[62:63], v[150:151]
	v_pk_fma_f32 v[60:61], v[140:141], v[60:61], v[148:149]
	v_pk_fma_f32 v[58:59], v[138:139], v[58:59], v[146:147]
	v_pk_fma_f32 v[56:57], v[136:137], v[56:57], v[144:145]
	v_pk_fma_f32 v[54:55], v[134:135], v[54:55], v[158:159]
	v_pk_fma_f32 v[52:53], v[132:133], v[52:53], v[156:157]
	v_pk_fma_f32 v[50:51], v[130:131], v[50:51], v[154:155]
	v_pk_fma_f32 v[48:49], v[128:129], v[48:49], v[152:153]
	v_add_u32_e32 v144, 0x90, v220
	ds_read_b32 v160, v237 offset:4672
	v_ashrrev_i32_e32 v145, 31, v144
	v_lshlrev_b64 v[144:145], 11, v[144:145]
	v_readlane_b32 s4, v255, 14
	v_lshl_add_u64 v[204:205], v[144:145], 0, v[174:175]
	v_readlane_b32 s5, v255, 15
	s_and_b64 vcc, exec, s[24:25]
	s_nop 0
	v_lshl_add_u64 v[210:211], v[204:205], 1, s[4:5]
	s_cbranch_vccz .LBB0_690
	s_waitcnt vmcnt(1)
	v_mov_b32_e32 v144, v240
	v_mov_b32_e32 v145, v241
	v_mov_b32_e32 v146, v242
	v_mov_b32_e32 v147, v243
	v_lshlrev_b32_e32 v148, 16, v144
	v_and_b32_e32 v149, 0xffff0000, v144
	v_lshlrev_b32_e32 v150, 16, v145
	v_and_b32_e32 v151, 0xffff0000, v145
	v_lshlrev_b32_e32 v144, 16, v146
	v_and_b32_e32 v145, 0xffff0000, v146
	v_lshlrev_b32_e32 v146, 16, v147
	v_and_b32_e32 v147, 0xffff0000, v147
	s_cbranch_execnz .LBB0_634

.LBB0_634:
	v_readlane_b32 s4, v255, 14
	v_or_b32_e32 v208, 0x80, v204
	v_mov_b32_e32 v209, v205
	v_readlane_b32 s5, v255, 15
	s_and_b64 vcc, exec, s[24:25]
	s_nop 0
	v_lshl_add_u64 v[214:215], v[208:209], 1, s[4:5]
	s_cbranch_vccz .LBB0_691
	s_waitcnt vmcnt(0)
	v_mov_b32_e32 v152, v244
	v_mov_b32_e32 v153, v245
	v_mov_b32_e32 v154, v246
	v_mov_b32_e32 v155, v247
	v_lshlrev_b32_e32 v156, 16, v152
	v_and_b32_e32 v157, 0xffff0000, v152
	v_lshlrev_b32_e32 v158, 16, v153
	v_and_b32_e32 v159, 0xffff0000, v153
	v_lshlrev_b32_e32 v152, 16, v154
	v_and_b32_e32 v153, 0xffff0000, v154
	v_lshlrev_b32_e32 v154, 16, v155
	v_and_b32_e32 v155, 0xffff0000, v155
	s_cbranch_execnz .LBB0_637

.LBB0_637:
	s_waitcnt lgkmcnt(0)
	v_pk_mul_f32 v[44:45], v[44:45], v[160:161] op_sel_hi:[1,0]
	v_pk_mul_f32 v[46:47], v[46:47], v[160:161] op_sel_hi:[1,0]
	v_pk_mul_f32 v[40:41], v[40:41], v[160:161] op_sel_hi:[1,0]
	v_pk_mul_f32 v[42:43], v[42:43], v[160:161] op_sel_hi:[1,0]
	v_pk_mul_f32 v[36:37], v[36:37], v[160:161] op_sel_hi:[1,0]
	v_pk_mul_f32 v[38:39], v[38:39], v[160:161] op_sel_hi:[1,0]
	v_pk_mul_f32 v[32:33], v[32:33], v[160:161] op_sel_hi:[1,0]
	v_pk_mul_f32 v[34:35], v[34:35], v[160:161] op_sel_hi:[1,0]
	s_waitcnt vmcnt(0)
	v_pk_fma_f32 v[46:47], v[142:143], v[46:47], v[150:151]
	v_pk_fma_f32 v[44:45], v[140:141], v[44:45], v[148:149]
	v_pk_fma_f32 v[42:43], v[138:139], v[42:43], v[146:147]
	v_pk_fma_f32 v[40:41], v[136:137], v[40:41], v[144:145]
	v_pk_fma_f32 v[38:39], v[134:135], v[38:39], v[158:159]
	v_pk_fma_f32 v[36:37], v[132:133], v[36:37], v[156:157]
	v_pk_fma_f32 v[34:35], v[130:131], v[34:35], v[154:155]
	v_pk_fma_f32 v[32:33], v[128:129], v[32:33], v[152:153]
	v_add_u32_e32 v144, 0xa0, v220
	ds_read_b32 v160, v237 offset:4736
	v_ashrrev_i32_e32 v145, 31, v144
	v_lshlrev_b64 v[144:145], 11, v[144:145]
	v_readlane_b32 s4, v255, 14
	v_lshl_add_u64 v[212:213], v[144:145], 0, v[174:175]
	v_readlane_b32 s5, v255, 15
	s_and_b64 vcc, exec, s[24:25]
	s_nop 0
	v_lshl_add_u64 v[218:219], v[212:213], 1, s[4:5]
	s_cbranch_vccz .LBB0_692
	global_load_dwordx4 v[144:147], v[218:219], off
	global_load_dwordx4 v[152:155], v[218:219], off offset:256
	v_lshl_add_u64 v[252:253], v[218:219], 0, s[100:101]
	global_load_dwordx4 v[240:243], v[252:253], off
	global_load_dwordx4 v[244:247], v[252:253], off offset:256
	s_waitcnt vmcnt(3)
	v_lshlrev_b32_e32 v148, 16, v144
	v_and_b32_e32 v149, 0xffff0000, v144
	v_lshlrev_b32_e32 v150, 16, v145
	v_and_b32_e32 v151, 0xffff0000, v145
	v_lshlrev_b32_e32 v144, 16, v146
	v_and_b32_e32 v145, 0xffff0000, v146
	v_lshlrev_b32_e32 v146, 16, v147
	v_and_b32_e32 v147, 0xffff0000, v147
	s_cbranch_execnz .LBB0_640

.LBB0_640:
	v_readlane_b32 s4, v255, 14
	v_or_b32_e32 v216, 0x80, v212
	v_mov_b32_e32 v217, v213
	v_readlane_b32 s5, v255, 15
	s_and_b64 vcc, exec, s[24:25]
	s_nop 0
	v_lshl_add_u64 v[222:223], v[216:217], 1, s[4:5]
	s_cbranch_vccz .LBB0_693
	s_waitcnt vmcnt(2)
	v_lshlrev_b32_e32 v156, 16, v152
	v_and_b32_e32 v157, 0xffff0000, v152
	v_lshlrev_b32_e32 v158, 16, v153
	v_and_b32_e32 v159, 0xffff0000, v153
	v_lshlrev_b32_e32 v152, 16, v154
	v_and_b32_e32 v153, 0xffff0000, v154
	v_lshlrev_b32_e32 v154, 16, v155
	v_and_b32_e32 v155, 0xffff0000, v155
	s_cbranch_execnz .LBB0_643

.LBB0_643:
	s_waitcnt lgkmcnt(0)
	v_pk_mul_f32 v[28:29], v[28:29], v[160:161] op_sel_hi:[1,0]
	v_pk_mul_f32 v[30:31], v[30:31], v[160:161] op_sel_hi:[1,0]
	v_pk_mul_f32 v[24:25], v[24:25], v[160:161] op_sel_hi:[1,0]
	v_pk_mul_f32 v[26:27], v[26:27], v[160:161] op_sel_hi:[1,0]
	v_pk_mul_f32 v[20:21], v[20:21], v[160:161] op_sel_hi:[1,0]
	v_pk_mul_f32 v[22:23], v[22:23], v[160:161] op_sel_hi:[1,0]
	v_pk_mul_f32 v[16:17], v[16:17], v[160:161] op_sel_hi:[1,0]
	v_pk_mul_f32 v[18:19], v[18:19], v[160:161] op_sel_hi:[1,0]
	s_waitcnt vmcnt(0)
	v_pk_fma_f32 v[30:31], v[142:143], v[30:31], v[150:151]
	v_pk_fma_f32 v[28:29], v[140:141], v[28:29], v[148:149]
	v_pk_fma_f32 v[26:27], v[138:139], v[26:27], v[146:147]
	v_pk_fma_f32 v[24:25], v[136:137], v[24:25], v[144:145]
	v_pk_fma_f32 v[22:23], v[134:135], v[22:23], v[158:159]
	v_pk_fma_f32 v[20:21], v[132:133], v[20:21], v[156:157]
	v_pk_fma_f32 v[18:19], v[130:131], v[18:19], v[154:155]
	v_pk_fma_f32 v[16:17], v[128:129], v[16:17], v[152:153]
	v_add_u32_e32 v144, 0xb0, v220
	ds_read_b32 v160, v237 offset:4800
	v_ashrrev_i32_e32 v145, 31, v144
	v_lshlrev_b64 v[144:145], 11, v[144:145]
	v_readlane_b32 s4, v255, 14
	v_lshl_add_u64 v[220:221], v[144:145], 0, v[174:175]
	v_readlane_b32 s5, v255, 15
	s_and_b64 vcc, exec, s[24:25]
	s_nop 0
	v_lshl_add_u64 v[226:227], v[220:221], 1, s[4:5]
	s_cbranch_vccz .LBB0_694
	s_waitcnt vmcnt(1)
	v_mov_b32_e32 v144, v240
	v_mov_b32_e32 v145, v241
	v_mov_b32_e32 v146, v242
	v_mov_b32_e32 v147, v243
	v_lshlrev_b32_e32 v148, 16, v144
	v_and_b32_e32 v149, 0xffff0000, v144
	v_lshlrev_b32_e32 v150, 16, v145
	v_and_b32_e32 v151, 0xffff0000, v145
	v_lshlrev_b32_e32 v144, 16, v146
	v_and_b32_e32 v145, 0xffff0000, v146
	v_lshlrev_b32_e32 v146, 16, v147
	v_and_b32_e32 v147, 0xffff0000, v147
	s_cbranch_execnz .LBB0_646

.LBB0_646:
	v_readlane_b32 s4, v255, 14
	v_or_b32_e32 v224, 0x80, v220
	v_mov_b32_e32 v225, v221
	v_readlane_b32 s5, v255, 15
	s_and_b64 vcc, exec, s[24:25]
	s_nop 0
	v_lshl_add_u64 v[228:229], v[224:225], 1, s[4:5]
	s_cbranch_vccz .LBB0_695
	s_waitcnt vmcnt(0)
	v_mov_b32_e32 v152, v244
	v_mov_b32_e32 v153, v245
	v_mov_b32_e32 v154, v246
	v_mov_b32_e32 v155, v247
	v_lshlrev_b32_e32 v156, 16, v152
	v_and_b32_e32 v157, 0xffff0000, v152
	v_lshlrev_b32_e32 v158, 16, v153
	v_and_b32_e32 v159, 0xffff0000, v153
	v_lshlrev_b32_e32 v152, 16, v154
	v_and_b32_e32 v153, 0xffff0000, v154
	v_lshlrev_b32_e32 v154, 16, v155
	v_and_b32_e32 v155, 0xffff0000, v155
	s_cbranch_execnz .LBB0_649
